# v18 + strategy 7.3 on HGRN pass 2: the four dwordx2 output stores per chunk widened to two dwordx4 via v_permlane16_swap (16 rows x 64 B per store)
# speedup vs baseline: 1.0090x; 1.0058x over previous
; #define LAS __attribute__((address_space(3)))
; __device__ __forceinline__ f32x4 mfma16(bf16x8 a, bf16x8 b, f32x4 c) { return __builtin_amdgcn_mfma_f32_16x16x32_bf16(a, b, c, 0, 0, 0); }
; template <bool FULL>
; __device__ __forceinline__ void hgrn_pass(int wv, const Args& a, int l, LAS unsigned char* lds, int item, bool dmy) {
;     ...
;         {
;             const f32x4 dd = *(const LAS f32x4*)(lds + HG_DV + (wid * 16 + 4 * fq) * 4);
; #pragma unroll
;             for (int j = 0; j < 8; ++j) sacc[j] = sacc[j] * dd;
; #pragma unroll
;             for (int k2 = 0; k2 < 2; ++k2) {
;                 const bf16x8 av = lds_ld16(lds + HG_KTT + ((wid * 16 + fr) * 72 + k2 * 32 + 8 * fq) * 2);
; #pragma unroll
;                 for (int j = 0; j < 8; ++j) { const bf16x8 bv = lds_ld16(lds + HG_VTT + ((j * 16 + fr) * 72 + k2 * 32 + 8 * fq) * 2); sacc[j] = mfma16(av, bv, sacc[j]); }
;             }
;         }
.LBB0_474:
	s_or_b64 exec, exec, s[24:25]
	s_waitcnt vmcnt(54)
	v_lshlrev_b32_e32 v32, 16, v187
	v_or_b32_sdwa v228, v32, v184 dst_sel:DWORD dst_unused:UNUSED_PAD src0_sel:DWORD src1_sel:WORD_0
	s_waitcnt vmcnt(52)
	v_lshlrev_b32_e32 v32, 16, v188
	s_waitcnt vmcnt(50) lgkmcnt(0)
	v_lshlrev_b32_e32 v33, 16, v198
	v_add_u32_e32 v184, 0x21000, v149
	v_or_b32_sdwa v32, v32, v185 dst_sel:DWORD dst_unused:UNUSED_PAD src0_sel:DWORD src1_sel:WORD_0
	v_or_b32_sdwa v181, v33, v186 dst_sel:DWORD dst_unused:UNUSED_PAD src0_sel:DWORD src1_sel:WORD_0
	ds_read_b128 v[184:187], v184
	s_waitcnt vmcnt(48)
	v_lshlrev_b32_e32 v33, 16, v201
	v_or_b32_sdwa v223, v33, v200 dst_sel:DWORD dst_unused:UNUSED_PAD src0_sel:DWORD src1_sel:WORD_0
	s_waitcnt vmcnt(46)
	v_lshlrev_b32_e32 v33, 16, v204
	s_waitcnt vmcnt(44)
	v_lshlrev_b32_e32 v34, 16, v205
	v_or_b32_sdwa v33, v33, v202 dst_sel:DWORD dst_unused:UNUSED_PAD src0_sel:DWORD src1_sel:WORD_0
	v_or_b32_sdwa v180, v34, v203 dst_sel:DWORD dst_unused:UNUSED_PAD src0_sel:DWORD src1_sel:WORD_0
	s_waitcnt lgkmcnt(0)
	v_pk_mul_f32 v[2:3], v[2:3], v[186:187]
	v_pk_mul_f32 v[0:1], v[0:1], v[184:185]
	v_pk_mul_f32 v[6:7], v[6:7], v[186:187]
	v_pk_mul_f32 v[4:5], v[4:5], v[184:185]
	v_pk_mul_f32 v[10:11], v[10:11], v[186:187]
	v_pk_mul_f32 v[8:9], v[8:9], v[184:185]
	v_pk_mul_f32 v[14:15], v[14:15], v[186:187]
	v_pk_mul_f32 v[12:13], v[12:13], v[184:185]
	v_pk_mul_f32 v[18:19], v[18:19], v[186:187]
	v_pk_mul_f32 v[16:17], v[16:17], v[184:185]
	v_pk_mul_f32 v[22:23], v[22:23], v[186:187]
	v_pk_mul_f32 v[20:21], v[20:21], v[184:185]
	v_pk_mul_f32 v[26:27], v[26:27], v[186:187]
	v_pk_mul_f32 v[24:25], v[24:25], v[184:185]
	v_pk_mul_f32 v[30:31], v[30:31], v[186:187]
	v_pk_mul_f32 v[28:29], v[28:29], v[184:185]
	ds_read_b128 v[184:187], v148 offset:52224
	ds_read_b128 v[200:203], v158
	s_waitcnt lgkmcnt(0)
	v_mfma_f32_16x16x32_bf16 v[0:3], v[184:187], v[200:203], v[0:3]
	ds_read_b128 v[200:203], v159
	s_waitcnt vmcnt(38)
	v_lshlrev_b32_e32 v35, 16, v211
	s_waitcnt vmcnt(32)
	v_lshlrev_b32_e32 v36, 16, v217
	s_waitcnt lgkmcnt(0)
	v_mfma_f32_16x16x32_bf16 v[4:7], v[184:187], v[200:203], v[4:7]
	ds_read_b128 v[200:203], v160
	s_waitcnt vmcnt(26)
	v_lshlrev_b32_e32 v37, 16, v240
	s_waitcnt vmcnt(20)
	v_lshlrev_b32_e32 v38, 16, v247
	s_waitcnt lgkmcnt(0)
	v_mfma_f32_16x16x32_bf16 v[8:11], v[184:187], v[200:203], v[8:11]
	ds_read_b128 v[200:203], v161
	s_waitcnt vmcnt(14)
	v_lshlrev_b32_e32 v39, 16, v224
	v_lshlrev_b32_e32 v34, 16, v209
	s_waitcnt lgkmcnt(0)
	v_mfma_f32_16x16x32_bf16 v[12:15], v[184:187], v[200:203], v[12:15]
	ds_read_b128 v[200:203], v162
	v_or_b32_sdwa v179, v35, v208 dst_sel:DWORD dst_unused:UNUSED_PAD src0_sel:DWORD src1_sel:WORD_0
	v_lshlrev_b32_e32 v35, 16, v215
	s_waitcnt lgkmcnt(0)
	v_mfma_f32_16x16x32_bf16 v[16:19], v[184:187], v[200:203], v[16:19]
	ds_read_b128 v[200:203], v163
	v_or_b32_sdwa v178, v36, v214 dst_sel:DWORD dst_unused:UNUSED_PAD src0_sel:DWORD src1_sel:WORD_0
	v_lshlrev_b32_e32 v36, 16, v221
	s_waitcnt lgkmcnt(0)
	v_mfma_f32_16x16x32_bf16 v[20:23], v[184:187], v[200:203], v[20:23]
	ds_read_b128 v[200:203], v164
	v_or_b32_sdwa v177, v37, v220 dst_sel:DWORD dst_unused:UNUSED_PAD src0_sel:DWORD src1_sel:WORD_0
	v_lshlrev_b32_e32 v37, 16, v245
	s_waitcnt lgkmcnt(0)
	v_mfma_f32_16x16x32_bf16 v[24:27], v[184:187], v[200:203], v[24:27]
	ds_read_b128 v[200:203], v165
	v_or_b32_sdwa v176, v38, v244 dst_sel:DWORD dst_unused:UNUSED_PAD src0_sel:DWORD src1_sel:WORD_0
	v_lshlrev_b32_e32 v38, 16, v249
	s_waitcnt lgkmcnt(0)
	v_mfma_f32_16x16x32_bf16 v[28:31], v[184:187], v[200:203], v[28:31]
	ds_read_b128 v[184:187], v148 offset:52288
	ds_read_b128 v[200:203], v166
	v_or_b32_sdwa v175, v39, v229 dst_sel:DWORD dst_unused:UNUSED_PAD src0_sel:DWORD src1_sel:WORD_0
	s_waitcnt vmcnt(12)
	v_lshlrev_b32_e32 v39, 16, v233
	s_waitcnt lgkmcnt(0)
	v_mfma_f32_16x16x32_bf16 v[0:3], v[184:187], v[200:203], v[0:3]
	ds_read_b128 v[200:203], v167
	v_or_b32_sdwa v222, v34, v206 dst_sel:DWORD dst_unused:UNUSED_PAD src0_sel:DWORD src1_sel:WORD_0
	v_lshlrev_b32_e32 v34, 16, v210
	s_waitcnt lgkmcnt(0)
	v_mfma_f32_16x16x32_bf16 v[4:7], v[184:187], v[200:203], v[4:7]
	ds_read_b128 v[200:203], v168
	v_or_b32_sdwa v236, v35, v212 dst_sel:DWORD dst_unused:UNUSED_PAD src0_sel:DWORD src1_sel:WORD_0
	v_lshlrev_b32_e32 v35, 16, v216
	s_waitcnt lgkmcnt(0)
	v_mfma_f32_16x16x32_bf16 v[8:11], v[184:187], v[200:203], v[8:11]
	ds_read_b128 v[200:203], v169
	v_or_b32_sdwa v242, v36, v218 dst_sel:DWORD dst_unused:UNUSED_PAD src0_sel:DWORD src1_sel:WORD_0
	v_lshlrev_b32_e32 v36, 16, v239
	s_waitcnt lgkmcnt(0)
	v_mfma_f32_16x16x32_bf16 v[12:15], v[184:187], v[200:203], v[12:15]
	ds_read_b128 v[200:203], v170
	v_or_b32_sdwa v199, v37, v241 dst_sel:DWORD dst_unused:UNUSED_PAD src0_sel:DWORD src1_sel:WORD_0
	v_lshlrev_b32_e32 v37, 16, v246
	s_waitcnt lgkmcnt(0)
	v_mfma_f32_16x16x32_bf16 v[16:19], v[184:187], v[200:203], v[16:19]
	ds_read_b128 v[200:203], v171
	v_or_b32_sdwa v183, v38, v248 dst_sel:DWORD dst_unused:UNUSED_PAD src0_sel:DWORD src1_sel:WORD_0
	v_lshlrev_b32_e32 v38, 16, v251
	s_waitcnt lgkmcnt(0)
	v_mfma_f32_16x16x32_bf16 v[20:23], v[184:187], v[200:203], v[20:23]
	ds_read_b128 v[200:203], v172
	v_or_b32_sdwa v182, v39, v230 dst_sel:DWORD dst_unused:UNUSED_PAD src0_sel:DWORD src1_sel:WORD_0
	s_waitcnt vmcnt(10)
	v_lshlrev_b32_e32 v39, 16, v234
	s_waitcnt lgkmcnt(0)
	v_mfma_f32_16x16x32_bf16 v[24:27], v[184:187], v[200:203], v[24:27]
	ds_read_b128 v[200:203], v173
	s_waitcnt lgkmcnt(0)
	s_barrier
; __device__ __forceinline__ float bflo(unsigned u) { return __uint_as_float(u << 16); }
; __device__ __forceinline__ float bfhi(unsigned u) { return __uint_as_float(u & 0xffff0000u); }
; __device__ __forceinline__ unsigned pk2(float lo, float hi) { f32x2 v = {lo, hi}; bf2_t b = __builtin_convertvector(v, bf2_t); return __builtin_bit_cast(unsigned, b); }
; template <bool FULL>
; __device__ __forceinline__ void hgrn_pass(int wv, const Args& a, int l, LAS unsigned char* lds, int item, bool dmy) {
;     ...
;         __syncthreads();
;         if (FULL) {
;             const int t = ti * 16 + fr;
;             const float tot = SSQP[t] + SSQP[64 + t];
;             const float rs = rsqrtf(tot * (1.f / 128.f) + EPS);
;             const size_t orow = row_base + (size_t)c * 64 + t;
; #pragma unroll
;             for (int jj = 0; jj < 4; ++jj) {
;                 const int dv0 = (dvh * 4 + jj) * 16 + 4 * fq;
;                 const u32x2 hg = cHG[jj];
;                 const float o0 = oacc[jj][0] * rs * gn[jj][0] * bflo(hg.x), o1 = oacc[jj][1] * rs * gn[jj][1] * bfhi(hg.x), o2 = oacc[jj][2] * rs * gn[jj][2] * bflo(hg.y), o3 = oacc[jj][3] * rs * gn[jj][3] * bfhi(hg.y);
;                 u32x2 w; w.x = pk2(o0, o1); w.y = pk2(o2, o3);
;                 *(u32x2*)(OA + orow * DM + h * 128 + dv0) = w;
;             }
	v_mfma_f32_16x16x32_bf16 v[28:31], v[184:187], v[200:203], v[28:31]
	ds_read2st64_b32 v[184:185], v94 offset1:1
	s_waitcnt vmcnt(8)
	v_lshlrev_b32_e32 v174, 16, v235
	v_or_b32_sdwa v34, v34, v207 dst_sel:DWORD dst_unused:UNUSED_PAD src0_sel:DWORD src1_sel:WORD_0
	v_or_b32_sdwa v35, v35, v213 dst_sel:DWORD dst_unused:UNUSED_PAD src0_sel:DWORD src1_sel:WORD_0
	v_or_b32_sdwa v36, v36, v219 dst_sel:DWORD dst_unused:UNUSED_PAD src0_sel:DWORD src1_sel:WORD_0
	s_waitcnt lgkmcnt(0)
	v_add_f32_e32 v184, v184, v185
	v_fmamk_f32 v184, v184, 0x3c000000, v226
	v_cmp_gt_f32_e32 vcc, s33, v184
	v_mul_f32_e32 v185, 0x4b800000, v184
	v_or_b32_sdwa v37, v37, v243 dst_sel:DWORD dst_unused:UNUSED_PAD src0_sel:DWORD src1_sel:WORD_0
	v_cndmask_b32_e32 v184, v184, v185, vcc
	v_rsq_f32_e32 v184, v184
	v_or_b32_sdwa v38, v38, v250 dst_sel:DWORD dst_unused:UNUSED_PAD src0_sel:DWORD src1_sel:WORD_0
	v_or_b32_sdwa v39, v39, v231 dst_sel:DWORD dst_unused:UNUSED_PAD src0_sel:DWORD src1_sel:WORD_0
	v_or_b32_sdwa v174, v174, v232 dst_sel:DWORD dst_unused:UNUSED_PAD src0_sel:DWORD src1_sel:WORD_0
	v_mul_f32_e32 v185, 0x45800000, v184
	v_cndmask_b32_e32 v184, v184, v185, vcc
	v_pk_mul_f32 v[64:65], v[64:65], v[184:185] op_sel_hi:[1,0]
	v_pk_mul_f32 v[66:67], v[66:67], v[184:185] op_sel_hi:[1,0]
	s_waitcnt vmcnt(7)
	v_pk_mul_f32 v[64:65], v[68:69], v[64:65]
	s_waitcnt vmcnt(5)
	v_lshlrev_b32_e32 v68, 16, v86
	v_and_b32_e32 v69, 0xffff0000, v86
	v_pk_mul_f32 v[60:61], v[60:61], v[184:185] op_sel_hi:[1,0]
	v_pk_mul_f32 v[44:45], v[44:45], v[184:185] op_sel_hi:[1,0]
	v_pk_mul_f32 v[64:65], v[64:65], v[68:69]
	v_pk_mul_f32 v[66:67], v[70:71], v[66:67]
	v_lshlrev_b32_e32 v68, 16, v87
	v_and_b32_e32 v69, 0xffff0000, v87
	v_pk_mul_f32 v[56:57], v[56:57], v[60:61]
	s_waitcnt vmcnt(4)
	v_lshlrev_b32_e32 v60, 16, v84
	v_and_b32_e32 v61, 0xffff0000, v84
	v_pk_mul_f32 v[48:49], v[48:49], v[184:185] op_sel_hi:[1,0]
	s_waitcnt vmcnt(0)
	v_pk_mul_f32 v[40:41], v[40:41], v[44:45]
	v_lshlrev_b32_e32 v44, 16, v80
	v_and_b32_e32 v45, 0xffff0000, v80
	v_pk_mul_f32 v[66:67], v[66:67], v[68:69]
	v_pk_mul_f32 v[56:57], v[56:57], v[60:61]
	v_pk_mul_f32 v[60:61], v[62:63], v[184:185] op_sel_hi:[1,0]
	v_pk_mul_f32 v[48:49], v[52:53], v[48:49]
	v_lshlrev_b32_e32 v52, 16, v82
	v_and_b32_e32 v53, 0xffff0000, v82
	v_pk_mul_f32 v[50:51], v[50:51], v[184:185] op_sel_hi:[1,0]
	v_pk_mul_f32 v[40:41], v[40:41], v[44:45]
	v_pk_mul_f32 v[44:45], v[46:47], v[184:185] op_sel_hi:[1,0]
	v_cvt_pk_bf16_f32 v64, v64, v65
	v_cvt_pk_bf16_f32 v65, v66, v67
	v_lshl_add_u64 v[66:67], v[78:79], 0, s[26:27]
	v_pk_mul_f32 v[58:59], v[58:59], v[60:61]
	v_lshlrev_b32_e32 v60, 16, v85
	v_and_b32_e32 v61, 0xffff0000, v85
	v_pk_mul_f32 v[48:49], v[48:49], v[52:53]
	v_pk_mul_f32 v[50:51], v[54:55], v[50:51]
	v_lshlrev_b32_e32 v52, 16, v83
	v_and_b32_e32 v53, 0xffff0000, v83
	v_pk_mul_f32 v[42:43], v[42:43], v[44:45]
	v_lshlrev_b32_e32 v44, 16, v81
	v_and_b32_e32 v45, 0xffff0000, v81
	s_add_u32 s26, s26, 0x20000
	v_pk_mul_f32 v[58:59], v[58:59], v[60:61]
	v_pk_mul_f32 v[50:51], v[50:51], v[52:53]
	v_pk_mul_f32 v[42:43], v[42:43], v[44:45]
	s_addc_u32 s27, s27, 0
	s_add_i32 s47, s47, 64
	v_cvt_pk_bf16_f32 v56, v56, v57
	v_cvt_pk_bf16_f32 v57, v58, v59
	v_cvt_pk_bf16_f32 v48, v48, v49
	v_cvt_pk_bf16_f32 v49, v50, v51
	v_cvt_pk_bf16_f32 v40, v40, v41
	v_cvt_pk_bf16_f32 v41, v42, v43
	s_cmp_lg_u32 s26, 0x200000
	v_mbcnt_lo_u32_b32 v42, -1, 0
	v_mbcnt_hi_u32_b32 v42, -1, v42
	v_bfe_u32 v42, v42, 4, 1
	v_mul_u32_u24_e32 v42, 24, v42
	v_mov_b32_e32 v43, 0
	v_lshl_add_u64 v[66:67], v[42:43], 0, v[66:67]
	v_mov_b32_e32 v60, v64
	v_mov_b32_e32 v61, v65
	v_mov_b32_e32 v62, v56
	v_mov_b32_e32 v63, v57
	v_mov_b32_e32 v52, v48
	v_mov_b32_e32 v53, v49
	v_mov_b32_e32 v54, v40
	v_mov_b32_e32 v55, v41
	s_nop 1
	v_permlane16_swap_b32_e32 v60, v62
	v_permlane16_swap_b32_e32 v61, v63
	v_permlane16_swap_b32_e32 v52, v54
	v_permlane16_swap_b32_e32 v53, v55
	global_store_dwordx4 v[66:67], v[60:63], off
	global_store_dwordx4 v[66:67], v[52:55], off offset:64
	s_cbranch_scc0 .LBB0_479
